# v40 + XCD leaders poll the monotonic TOP counter directly instead of a separate TOPGEN word (one fewer cross-XCD atomic hop per grid barrier)
# baseline (speedup 1.0000x reference)
; __device__ __forceinline__ unsigned xb_ld(unsigned* p)              { return __hip_atomic_load(p, __ATOMIC_RELAXED, __HIP_MEMORY_SCOPE_AGENT); }
; __device__ __forceinline__ unsigned xb_add(unsigned* p, unsigned v) { return __hip_atomic_fetch_add(p, v, __ATOMIC_RELAXED, __HIP_MEMORY_SCOPE_AGENT); }
; #define XB_SPIN(cond, bar) do { unsigned _sp = 0; while (cond) { __builtin_amdgcn_s_sleep(1); \
;     if ((++_sp & 255u) == 0u) { if (xb_ld(&(bar)[XB_TMO])) break; if (_sp > XB_SPIN_CAP) { atomicAdd(&(bar)[XB_TMO], 1u); break; } } } } while (0)
; __device__ __forceinline__ void xcd_barrier(unsigned* bar, volatile LAS unsigned* st) {
;     ...
;             const unsigned og = xb_add(&bar[XB_TOP], 1u);
;             const unsigned tg = og / nx;
;             if (og + 1u == (tg + 1u) * nx) xb_add(&bar[XB_TOPGEN], 1u);
;             else XB_SPIN(xb_ld(&bar[XB_TOPGEN]) == tg, bar);
.LBB0_515:
	s_or_b64 exec, exec, s[8:9]
	s_waitcnt vmcnt(0)
	v_readfirstlane_b32 s6, v3
	v_sub_u32_e32 v4, 0, v2
	s_mov_b64 s[10:11], 0
	v_add_u32_e32 v3, s6, v0
	v_cvt_f32_u32_e32 v0, v2
	s_add_u32 s6, s42, 0x31049400
	s_addc_u32 s7, s43, 0
	v_rcp_iflag_f32_e32 v0, v0
	s_nop 0
	v_mul_f32_e32 v0, 0x4f7ffffe, v0
	v_cvt_u32_f32_e32 v0, v0
	v_mul_lo_u32 v4, v4, v0
	v_mul_hi_u32 v4, v0, v4
	v_add_u32_e32 v0, v0, v4
	v_mul_hi_u32 v0, v3, v0
	v_mul_lo_u32 v4, v0, v2
	v_sub_u32_e32 v4, v3, v4
	v_cmp_ge_u32_e32 vcc, v4, v2
	v_add_u32_e32 v5, 1, v0
	v_add_u32_e32 v3, 1, v3
	v_cndmask_b32_e32 v0, v0, v5, vcc
	v_sub_u32_e32 v5, v4, v2
	v_cndmask_b32_e32 v4, v4, v5, vcc
	v_cmp_ge_u32_e32 vcc, v4, v2
	v_add_u32_e32 v4, 1, v0
	s_nop 0
	v_cndmask_b32_e32 v0, v0, v4, vcc
	v_mul_lo_u32 v4, v2, v0
	v_add_u32_e32 v2, v4, v2
	v_mov_b32_e32 v5, v2
	v_cmp_ne_u32_e32 vcc, v3, v2
	v_mov_b64_e32 v[2:3], s[6:7]
	s_and_saveexec_b64 s[8:9], vcc
	s_cbranch_execz .LBB0_527
	global_load_dword v2, v1, s[6:7] sc1
	s_mov_b64 s[16:17], 0
	s_waitcnt vmcnt(0)
	v_cmp_lt_u32_e32 vcc, v2, v5
	s_and_saveexec_b64 s[12:13], vcc
	s_cbranch_execz .LBB0_526
	s_add_u32 s10, s42, 0x31046200
	s_addc_u32 s11, s43, 0
	s_mov_b32 s24, 1
	s_mov_b64 s[14:15], 0
	s_branch .LBB0_519

; __device__ __forceinline__ unsigned xb_ld(unsigned* p)              { return __hip_atomic_load(p, __ATOMIC_RELAXED, __HIP_MEMORY_SCOPE_AGENT); }
; #define XB_SPIN(cond, bar) do { unsigned _sp = 0; while (cond) { __builtin_amdgcn_s_sleep(1); \
;     if ((++_sp & 255u) == 0u) { if (xb_ld(&(bar)[XB_TMO])) break; if (_sp > XB_SPIN_CAP) { atomicAdd(&(bar)[XB_TMO], 1u); break; } } } } while (0)
; __device__ __forceinline__ void xcd_barrier(unsigned* bar, volatile LAS unsigned* st) {
;     ...
;             else XB_SPIN(xb_ld(&bar[XB_TOPGEN]) == tg, bar);
.LBB0_523:
	global_load_dword v2, v1, s[6:7] sc1
	s_add_i32 s24, s24, 1
	s_mov_b64 s[20:21], -1
	s_waitcnt vmcnt(0)
	v_cmp_ge_u32_e32 vcc, v2, v5
	s_orn2_b64 s[18:19], vcc, exec
	s_branch .LBB0_518
